# neighbourhood-attention tile loop: same softmax/PV interleave and scale-into-exp fold as the dilated loop
# baseline (speedup 1.0000x reference)
;     __device__ __forceinline__ float bias(int qi, int half, int t, int jc) const {
;         const int j = jc + 4 * half;
;         const int r = R + (qi >> 6), c = qi & 63, kr = kr_lo + t, c0 = min(max(c - 8, 0), 48);
;         const bool ok = (j >= c0) && (j < c0 + 16);
;         const int idx = min(max((kr - r + 7) * 31 + (j - c + 15), 0), 15 * 31 - 1);
;         const float bv = rpb[idx];
;         return ok ? bv : -__builtin_inff();
;     }
;     __device__ __forceinline__ void fill(f32x16& S0, f32x16& S1, int qi, int half, int t, int) const {
; #pragma unroll
;         for (int i = 0; i < 16; ++i) { const int jc = 8 * (i >> 2) + (i & 3); S0[i] = bias(qi, half, t, jc); S1[i] = bias(qi, half, t, 32 + jc); }
.LBB0_463:
	s_add_i32 s51, s42, s49
	s_cmp_lt_u32 s51, s46
	s_cselect_b64 vcc, -1, 0
	s_cmp_gt_u32 s51, s47
	s_cselect_b64 s[52:53], -1, 0
	s_or_b64 s[52:53], vcc, s[52:53]
	s_and_b64 vcc, exec, s[52:53]
	s_cbranch_vccnz .LBB0_467
	v_subrev_u32_e32 v2, 59, v172
	v_subrev_u32_e32 v3, 27, v172
	v_subrev_u32_e32 v4, 58, v172
	v_subrev_u32_e32 v5, 26, v172
	v_subrev_u32_e32 v6, 57, v172
	v_subrev_u32_e32 v7, 25, v172
	v_subrev_u32_e32 v8, 56, v172
	v_subrev_u32_e32 v9, 24, v172
	v_med3_i32 v2, v2, 0, v239
	s_add_i32 vcc_lo, 0, 0x18000
	v_med3_i32 v3, v3, 0, v239
	v_med3_i32 v4, v4, 0, v239
	v_med3_i32 v5, v5, 0, v239
	v_med3_i32 v6, v6, 0, v239
	v_med3_i32 v7, v7, 0, v239
	v_med3_i32 v8, v8, 0, v239
	v_med3_i32 v9, v9, 0, v239
	v_readlane_b32 s52, v250, 1
	v_lshl_add_u32 v2, v2, 2, vcc_lo
	v_lshl_add_u32 v3, v3, 2, vcc_lo
	v_lshl_add_u32 v4, v4, 2, vcc_lo
	v_lshl_add_u32 v5, v5, 2, vcc_lo
	v_lshl_add_u32 v6, v6, 2, vcc_lo
	v_lshl_add_u32 v7, v7, 2, vcc_lo
	v_lshl_add_u32 v8, v8, 2, vcc_lo
	v_lshl_add_u32 v9, v9, 2, vcc_lo
	v_readlane_b32 s53, v250, 2
	ds_read_b32 v2, v2
	ds_read_b32 v3, v3
	ds_read_b32 v4, v4
	ds_read_b32 v5, v5
	ds_read_b32 v6, v6
	ds_read_b32 v7, v7
	ds_read_b32 v8, v8
	ds_read_b32 v9, v9
	s_waitcnt lgkmcnt(6)
	v_cndmask_b32_e64 v80, v238, v3, s[52:53]
	v_readlane_b32 s52, v250, 3
	v_readlane_b32 s53, v250, 4
	v_cndmask_b32_e64 v96, v2, v238, s[36:37]
	v_subrev_u32_e32 v2, 51, v172
	s_waitcnt lgkmcnt(5)
	v_cndmask_b32_e64 v97, v4, v238, s[52:53]
	v_readlane_b32 s52, v250, 5
	v_readlane_b32 s53, v250, 6
	v_subrev_u32_e32 v3, 19, v172
	v_subrev_u32_e32 v4, 50, v172
	s_waitcnt lgkmcnt(4)
	v_cndmask_b32_e64 v81, v238, v5, s[52:53]
	v_readlane_b32 s52, v250, 7
	v_readlane_b32 s53, v250, 8
	v_subrev_u32_e32 v5, 18, v172
	v_med3_i32 v2, v2, 0, v239
	s_waitcnt lgkmcnt(3)
	v_cndmask_b32_e64 v98, v6, v238, s[52:53]
	v_readlane_b32 s52, v250, 9
	v_readlane_b32 s53, v250, 10
	v_subrev_u32_e32 v6, 49, v172
	v_med3_i32 v3, v3, 0, v239
	s_waitcnt lgkmcnt(2)
	v_cndmask_b32_e64 v82, v238, v7, s[52:53]
	v_readlane_b32 s52, v250, 11
	v_readlane_b32 s53, v250, 12
	v_subrev_u32_e32 v7, 17, v172
	v_med3_i32 v4, v4, 0, v239
	s_waitcnt lgkmcnt(1)
	v_cndmask_b32_e64 v99, v8, v238, s[52:53]
	v_readlane_b32 s52, v250, 13
	v_readlane_b32 s53, v250, 14
	v_subrev_u32_e32 v8, 48, v172
	v_med3_i32 v5, v5, 0, v239
	s_waitcnt lgkmcnt(0)
	v_cndmask_b32_e64 v83, v238, v9, s[52:53]
	v_add_u32_e32 v9, -16, v172
	v_med3_i32 v6, v6, 0, v239
	v_med3_i32 v7, v7, 0, v239
	v_med3_i32 v8, v8, 0, v239
	v_med3_i32 v9, v9, 0, v239
	v_lshl_add_u32 v2, v2, 2, vcc_lo
	v_lshl_add_u32 v3, v3, 2, vcc_lo
	v_lshl_add_u32 v4, v4, 2, vcc_lo
	v_lshl_add_u32 v5, v5, 2, vcc_lo
	v_lshl_add_u32 v6, v6, 2, vcc_lo
	v_lshl_add_u32 v7, v7, 2, vcc_lo
	v_lshl_add_u32 v8, v8, 2, vcc_lo
	v_lshl_add_u32 v9, v9, 2, vcc_lo
	ds_read_b32 v2, v2
	ds_read_b32 v3, v3
	ds_read_b32 v4, v4
	ds_read_b32 v5, v5
	ds_read_b32 v6, v6
	ds_read_b32 v7, v7
	ds_read_b32 v8, v8
	ds_read_b32 v9, v9
	v_readlane_b32 s52, v250, 15
	v_readlane_b32 s53, v250, 16
	s_waitcnt lgkmcnt(6)
	v_cndmask_b32_e64 v84, v238, v3, s[54:55]
	s_waitcnt lgkmcnt(5)
	v_cndmask_b32_e64 v101, v4, v238, s[56:57]
	v_cndmask_b32_e64 v100, v2, v238, s[52:53]
	s_waitcnt lgkmcnt(4)
	v_cndmask_b32_e64 v85, v238, v5, s[58:59]
	s_waitcnt lgkmcnt(3)
	v_cndmask_b32_e64 v102, v6, v238, s[60:61]
	v_subrev_u32_e32 v2, 43, v172
	v_add_u32_e32 v3, -11, v172
	v_subrev_u32_e32 v4, 42, v172
	v_add_u32_e32 v5, -10, v172
	v_subrev_u32_e32 v6, 41, v172
	s_waitcnt lgkmcnt(2)
	v_cndmask_b32_e64 v86, v238, v7, s[62:63]
	s_waitcnt lgkmcnt(1)
	v_cndmask_b32_e64 v103, v8, v238, s[64:65]
	s_waitcnt lgkmcnt(0)
	v_cndmask_b32_e64 v87, v238, v9, s[40:41]
	v_med3_i32 v2, v2, 0, v239
	v_med3_i32 v3, v3, 0, v239
	v_med3_i32 v4, v4, 0, v239
	v_med3_i32 v5, v5, 0, v239
	v_med3_i32 v6, v6, 0, v239
	v_add_u32_e32 v7, -9, v172
	v_subrev_u32_e32 v8, 40, v172
	v_add_u32_e32 v9, -8, v172
	v_lshl_add_u32 v2, v2, 2, vcc_lo
	v_lshl_add_u32 v3, v3, 2, vcc_lo
	v_lshl_add_u32 v4, v4, 2, vcc_lo
	v_lshl_add_u32 v5, v5, 2, vcc_lo
	v_lshl_add_u32 v6, v6, 2, vcc_lo
	v_med3_i32 v7, v7, 0, v239
	v_med3_i32 v8, v8, 0, v239
	v_med3_i32 v9, v9, 0, v239
	v_lshl_add_u32 v7, v7, 2, vcc_lo
	v_lshl_add_u32 v8, v8, 2, vcc_lo
	v_lshl_add_u32 v9, v9, 2, vcc_lo
	ds_read_b32 v2, v2
	ds_read_b32 v3, v3
	ds_read_b32 v4, v4
	ds_read_b32 v10, v5
	ds_read_b32 v5, v6
	ds_read_b32 v11, v7
	ds_read_b32 v6, v8
	ds_read_b32 v12, v9
	s_waitcnt lgkmcnt(7)
	v_cndmask_b32_e64 v104, v238, v2, s[68:69]
	v_subrev_u32_e32 v2, 35, v172
	v_med3_i32 v2, v2, 0, v239
	s_waitcnt lgkmcnt(1)
	v_cndmask_b32_e64 v107, v238, v6, s[80:81]
	v_lshl_add_u32 v6, v2, 2, vcc_lo
	v_add_u32_e32 v2, -3, v172
	v_med3_i32 v2, v2, 0, v239
	v_lshl_add_u32 v7, v2, 2, vcc_lo
	v_subrev_u32_e32 v2, 34, v172
	v_med3_i32 v2, v2, 0, v239
	v_lshl_add_u32 v8, v2, 2, vcc_lo
	v_add_u32_e32 v2, -2, v172
	v_med3_i32 v2, v2, 0, v239
	v_lshl_add_u32 v9, v2, 2, vcc_lo
	v_subrev_u32_e32 v2, 33, v172
	v_med3_i32 v2, v2, 0, v239
	v_lshl_add_u32 v13, v2, 2, vcc_lo
	v_add_u32_e32 v2, -1, v172
	s_lshl_b32 s51, s50, 15
	v_med3_i32 v2, v2, 0, v239
	s_add_i32 s51, s51, 0
	v_lshl_add_u32 v14, v2, 2, vcc_lo
	v_subrev_u32_e32 v2, 32, v172
	v_add_u32_e32 v0, s51, v145
	v_med3_i32 v2, v2, 0, v239
	v_lshl_add_u32 v15, v2, 2, vcc_lo
	v_med3_i32 v2, v172, 0, v239
	v_add_u32_e32 v90, v0, v156
	v_cndmask_b32_e64 v88, v238, v3, s[70:71]
	v_cndmask_b32_e64 v105, v238, v4, s[72:73]
	v_cndmask_b32_e64 v106, v238, v5, s[76:77]
	v_lshl_add_u32 v89, v2, 2, vcc_lo
	ds_read_b128 v[2:5], v90
	ds_read_b32 v6, v6
	ds_read_b32 v92, v7
	ds_read_b32 v7, v8
	ds_read_b32 v93, v9
	ds_read_b32 v8, v13
	ds_read_b32 v13, v14
	ds_read_b32 v9, v15
	ds_read_b32 v14, v89
	s_waitcnt lgkmcnt(7)
; #define LAS __attribute__((address_space(3)))
; __device__ __forceinline__ unsigned pk2(float lo, float hi) { f32x2 v = {lo, hi}; bf16x2_t b = __builtin_convertvector(v, bf16x2_t); return __builtin_bit_cast(unsigned, b); }
; #define MFMA32(a, b, c) __builtin_amdgcn_mfma_f32_32x32x16_bf16((a), (b), (c), 0, 0, 0)
; template <int KSTEPS, class Pol>
; __device__ __forceinline__ void attn_pass(LAS unsigned char* lds, const Pol& P, const bf16_t* qb, int ldq, const bf16_t* kb, int ldk, const bf16_t* vb, int ldv,
;                                           float qs, f32x16 (&O)[4], float& m, float& l) {
;     ...
; #pragma unroll
;         for (int ks = 0; ks < KSTEPS; ++ks) {
;             const int so = ((2 * ks) ^ kx) << 4;
;             const bf16x8 a0 = *(const LAS bf16x8*)(Kb + so);
;             const bf16x8 a1 = *(const LAS bf16x8*)(Kb + 32 * KROWB + so);
;             S0 = MFMA32(a0, qf[ks], S0);
;             S1 = MFMA32(a1, qf[ks], S1);
;         }
;         S0 = S0 * qs; S1 = S1 * qs;
;         float mx = fmaxf(S0[0], S1[0]);
; #pragma unroll
;         for (int i = 1; i < 16; ++i) mx = fmaxf(fmaxf(mx, S0[i]), S1[i]);
;         mx = fmaxf(mx, __shfl_xor(mx, 32));
;         const float mnew = fmaxf(m, mx);
;         const float alpha = __builtin_amdgcn_exp2f(m - mnew);
;         m = mnew;
;         {
;             const f32x2 nm = {-mnew, -mnew};
; #pragma unroll
;             for (int i = 0; i < 16; i += 2) { const f32x2 a = (f32x2){S0[i], S0[i + 1]} + nm, b = (f32x2){S1[i], S1[i + 1]} + nm; S0[i] = a.x; S0[i + 1] = a.y; S1[i] = b.x; S1[i + 1] = b.y; }
;         }
;         f32x2 ls2 = {0.f, 0.f};
; #pragma unroll
;         for (int s = 0; s < 4; ++s) {
;             unsigned w[4];
; #pragma unroll
;             for (int e = 0; e < 4; ++e) {
;                 const int i = 8 * (s & 1) + 2 * e;
;                 f32x2 pv;
;                 pv.x = __builtin_amdgcn_exp2f(s < 2 ? S0[i] : S1[i]); pv.y = __builtin_amdgcn_exp2f(s < 2 ? S0[i + 1] : S1[i + 1]);
;                 ls2 = ls2 + pv;
;                 w[e] = pk2(pv.x, pv.y);
;             }
;             u32x4 wv; wv.x = w[0]; wv.y = w[1]; wv.z = w[2]; wv.w = w[3];
;             pf[s] = __builtin_bit_cast(bf16x8, wv);
;         }
;         l = l * alpha + (ls2.x + ls2.y);
;         if (__any(alpha != 1.0f)) {
; #pragma unroll
;             for (int blk = 0; blk < 4; ++blk) O[blk] = O[blk] * alpha;
;         }
	v_cndmask_b32_e64 v108, v238, v6, s[84:85]
	s_waitcnt lgkmcnt(5)
	v_cndmask_b32_e64 v109, v238, v7, s[88:89]
	s_waitcnt lgkmcnt(3)
	v_cndmask_b32_e64 v110, v238, v8, s[92:93]
	s_waitcnt lgkmcnt(1)
	v_cndmask_b32_e64 v111, v238, v9, s[96:97]
	ds_read_b128 v[6:9], v90 offset:8192
	v_cndmask_b32_e64 v89, v238, v10, s[74:75]
	v_cndmask_b32_e64 v90, v238, v11, s[78:79]
	v_cndmask_b32_e64 v91, v238, v12, s[82:83]
	v_cndmask_b32_e64 v92, v238, v92, s[86:87]
	v_cndmask_b32_e64 v93, v238, v93, s[90:91]
	v_cndmask_b32_e64 v94, v238, v13, s[94:95]
	s_waitcnt lgkmcnt(1)
	v_cndmask_b32_e64 v95, v238, v14, s[2:3]
	v_mfma_f32_32x32x16_bf16 v[96:111], v[2:5], v[112:115], v[96:111]
	v_and_b32_e32 v15, 64, v234
	v_xor_b32_e32 v14, 32, v234
	v_add_u32_e32 v15, 64, v15
	v_cmp_lt_i32_e32 vcc, v14, v15
	s_nop 1
	v_cndmask_b32_e32 v14, v234, v14, vcc
	s_waitcnt lgkmcnt(0)
	v_mfma_f32_32x32x16_bf16 v[80:95], v[6:9], v[112:115], v[80:95]
	v_add_u32_e32 v6, v0, v157
	ds_read_b128 v[2:5], v6
	ds_read_b128 v[6:9], v6 offset:8192
	v_add_u32_e32 v200, v0, v158
	ds_read_b128 v[192:195], v200
	ds_read_b128 v[196:199], v200 offset:8192
	v_lshlrev_b32_e32 v14, 2, v14
	s_waitcnt lgkmcnt(3)
	v_mfma_f32_32x32x16_bf16 v[96:111], v[2:5], v[116:119], v[96:111]
	s_waitcnt lgkmcnt(2)
	v_mfma_f32_32x32x16_bf16 v[80:95], v[6:9], v[116:119], v[80:95]
	v_add_u32_e32 v6, v0, v159
	ds_read_b128 v[2:5], v6
	ds_read_b128 v[6:9], v6 offset:8192
	s_waitcnt lgkmcnt(3)
	v_mfma_f32_32x32x16_bf16 v[96:111], v[192:195], v[120:123], v[96:111]
	s_waitcnt lgkmcnt(2)
	v_mfma_f32_32x32x16_bf16 v[80:95], v[196:199], v[120:123], v[80:95]
	v_add_u32_e32 v200, v0, v160
	ds_read_b128 v[192:195], v200
	ds_read_b128 v[196:199], v200 offset:8192
	s_waitcnt lgkmcnt(3)
	v_mfma_f32_32x32x16_bf16 v[96:111], v[2:5], v[124:127], v[96:111]
	s_waitcnt lgkmcnt(2)
	v_mfma_f32_32x32x16_bf16 v[80:95], v[6:9], v[124:127], v[80:95]
	v_add_u32_e32 v6, v0, v161
	ds_read_b128 v[2:5], v6
	ds_read_b128 v[6:9], v6 offset:8192
	s_waitcnt lgkmcnt(3)
	v_mfma_f32_32x32x16_bf16 v[96:111], v[192:195], v[128:131], v[96:111]
	s_waitcnt lgkmcnt(2)
	v_mfma_f32_32x32x16_bf16 v[80:95], v[196:199], v[128:131], v[80:95]
	v_add_u32_e32 v200, v0, v162
	ds_read_b128 v[192:195], v200
	ds_read_b128 v[196:199], v200 offset:8192
	s_waitcnt lgkmcnt(3)
	v_mfma_f32_32x32x16_bf16 v[96:111], v[2:5], v[132:135], v[96:111]
	s_waitcnt lgkmcnt(2)
	v_mfma_f32_32x32x16_bf16 v[80:95], v[6:9], v[132:135], v[80:95]
	v_add_u32_e32 v201, v0, v163
	ds_read_b128 v[2:5], v201
	ds_read_b128 v[6:9], v201 offset:8192
	s_waitcnt lgkmcnt(3)
	v_mfma_f32_32x32x16_bf16 v[96:111], v[192:195], v[136:139], v[96:111]
	s_waitcnt lgkmcnt(2)
	v_mfma_f32_32x32x16_bf16 v[80:95], v[196:199], v[136:139], v[80:95]
	s_waitcnt lgkmcnt(1)
	v_mfma_f32_32x32x16_bf16 v[96:111], v[2:5], v[140:143], v[96:111]
	s_waitcnt lgkmcnt(0)
	v_mfma_f32_32x32x16_bf16 v[80:95], v[6:9], v[140:143], v[80:95]
	v_add_u32_e32 v201, s51, v164
	v_add_u32_e32 v202, s51, v165
	v_add_u32_e32 v203, s51, v166
	v_add_u32_e32 v204, s51, v167
	ds_read_b64_tr_b16 v[192:193], v201 offset:16384
	ds_read_b64_tr_b16 v[194:195], v202 offset:2048
	ds_read_b64_tr_b16 v[196:197], v203 offset:16384
	ds_read_b64_tr_b16 v[198:199], v204 offset:2048
	v_add_u32_e32 v2, s51, v168
	v_add_u32_e32 v3, s51, v169
	v_add_u32_e32 v4, s51, v170
	v_add_u32_e32 v5, s51, v171
	v_max_f32_e32 v15, v96, v80
	v_max3_f32 v15, v15, v97, v81
	v_max3_f32 v15, v15, v98, v82
	v_max3_f32 v15, v15, v99, v83
	v_max3_f32 v15, v15, v100, v84
	v_max3_f32 v15, v15, v101, v85
	v_max3_f32 v15, v15, v102, v86
	v_max3_f32 v15, v15, v103, v87
	v_max3_f32 v15, v15, v104, v88
	v_max3_f32 v15, v15, v105, v89
	v_max3_f32 v15, v15, v106, v90
	v_max3_f32 v15, v15, v107, v91
	v_max3_f32 v15, v15, v108, v92
	v_max3_f32 v15, v15, v109, v93
	v_max3_f32 v15, v15, v110, v94
	v_max3_f32 v15, v15, v111, v95
	v_mul_f32_e64 v15, v15, s20
	ds_bpermute_b32 v14, v14, v15
	s_waitcnt lgkmcnt(0)
	v_max3_f32 v0, v175, v15, v14
	v_sub_f32_e32 v14, v175, v0
	v_exp_f32_e32 v14, v14
	s_nop 0
	v_cmp_neq_f32_e32 vcc, 1.0, v14
	s_cbranch_vccz .LBB0_466
	v_pk_mul_f32 v[78:79], v[78:79], v[14:15] op_sel_hi:[1,0]
	v_pk_mul_f32 v[76:77], v[76:77], v[14:15] op_sel_hi:[1,0]
	v_pk_mul_f32 v[74:75], v[74:75], v[14:15] op_sel_hi:[1,0]
	v_pk_mul_f32 v[72:73], v[72:73], v[14:15] op_sel_hi:[1,0]
	v_pk_mul_f32 v[70:71], v[70:71], v[14:15] op_sel_hi:[1,0]
	v_pk_mul_f32 v[68:69], v[68:69], v[14:15] op_sel_hi:[1,0]
	v_pk_mul_f32 v[66:67], v[66:67], v[14:15] op_sel_hi:[1,0]
	v_pk_mul_f32 v[64:65], v[64:65], v[14:15] op_sel_hi:[1,0]
	v_pk_mul_f32 v[62:63], v[62:63], v[14:15] op_sel_hi:[1,0]
	v_pk_mul_f32 v[60:61], v[60:61], v[14:15] op_sel_hi:[1,0]
	v_pk_mul_f32 v[58:59], v[58:59], v[14:15] op_sel_hi:[1,0]
	v_pk_mul_f32 v[56:57], v[56:57], v[14:15] op_sel_hi:[1,0]
	v_pk_mul_f32 v[54:55], v[54:55], v[14:15] op_sel_hi:[1,0]
	v_pk_mul_f32 v[52:53], v[52:53], v[14:15] op_sel_hi:[1,0]
	v_pk_mul_f32 v[50:51], v[50:51], v[14:15] op_sel_hi:[1,0]
	v_pk_mul_f32 v[48:49], v[48:49], v[14:15] op_sel_hi:[1,0]
	v_pk_mul_f32 v[46:47], v[46:47], v[14:15] op_sel_hi:[1,0]
	v_pk_mul_f32 v[44:45], v[44:45], v[14:15] op_sel_hi:[1,0]
	v_pk_mul_f32 v[42:43], v[42:43], v[14:15] op_sel_hi:[1,0]
	v_pk_mul_f32 v[40:41], v[40:41], v[14:15] op_sel_hi:[1,0]
	v_pk_mul_f32 v[38:39], v[38:39], v[14:15] op_sel_hi:[1,0]
	v_pk_mul_f32 v[36:37], v[36:37], v[14:15] op_sel_hi:[1,0]
	v_pk_mul_f32 v[34:35], v[34:35], v[14:15] op_sel_hi:[1,0]
	v_pk_mul_f32 v[32:33], v[32:33], v[14:15] op_sel_hi:[1,0]
	v_pk_mul_f32 v[30:31], v[30:31], v[14:15] op_sel_hi:[1,0]
	v_pk_mul_f32 v[28:29], v[28:29], v[14:15] op_sel_hi:[1,0]
	v_pk_mul_f32 v[26:27], v[26:27], v[14:15] op_sel_hi:[1,0]
	v_pk_mul_f32 v[24:25], v[24:25], v[14:15] op_sel_hi:[1,0]
	v_pk_mul_f32 v[22:23], v[22:23], v[14:15] op_sel_hi:[1,0]
	v_pk_mul_f32 v[20:21], v[20:21], v[14:15] op_sel_hi:[1,0]
	v_pk_mul_f32 v[18:19], v[18:19], v[14:15] op_sel_hi:[1,0]
	v_pk_mul_f32 v[16:17], v[16:17], v[14:15] op_sel_hi:[1,0]
; #define LAS __attribute__((address_space(3)))
; __device__ __forceinline__ unsigned pk2(float lo, float hi) { f32x2 v = {lo, hi}; bf16x2_t b = __builtin_convertvector(v, bf16x2_t); return __builtin_bit_cast(unsigned, b); }
; #define MFMA32(a, b, c) __builtin_amdgcn_mfma_f32_32x32x16_bf16((a), (b), (c), 0, 0, 0)
; template <int KSTEPS, class Pol>
; __device__ __forceinline__ void attn_pass(LAS unsigned char* lds, const Pol& P, const bf16_t* qb, int ldq, const bf16_t* kb, int ldk, const bf16_t* vb, int ldv,
;                                           float qs, f32x16 (&O)[4], float& m, float& l) {
;     ...
;             const f32x2 nm = {-mnew, -mnew};
; #pragma unroll
;             for (int i = 0; i < 16; i += 2) { const f32x2 a = (f32x2){S0[i], S0[i + 1]} + nm, b = (f32x2){S1[i], S1[i + 1]} + nm; S0[i] = a.x; S0[i + 1] = a.y; S1[i] = b.x; S1[i + 1] = b.y; }
;         }
;         f32x2 ls2 = {0.f, 0.f};
; #pragma unroll
;         for (int s = 0; s < 4; ++s) {
;             unsigned w[4];
; #pragma unroll
;             for (int e = 0; e < 4; ++e) {
;                 const int i = 8 * (s & 1) + 2 * e;
;                 f32x2 pv;
;                 pv.x = __builtin_amdgcn_exp2f(s < 2 ? S0[i] : S1[i]); pv.y = __builtin_amdgcn_exp2f(s < 2 ? S0[i + 1] : S1[i + 1]);
;                 ls2 = ls2 + pv;
;                 w[e] = pk2(pv.x, pv.y);
;             }
;             u32x4 wv; wv.x = w[0]; wv.y = w[1]; wv.z = w[2]; wv.w = w[3];
;             pf[s] = __builtin_bit_cast(bf16x8, wv);
;         }
;         l = l * alpha + (ls2.x + ls2.y);
;     ...
;     auto pv_acc = [&](int st) __attribute__((always_inline)) {
;         LAS unsigned char* Vb = lds + st * A_STAGE;
; #pragma unroll
;         for (int s = 0; s < 4; ++s) {
; #pragma unroll
;             for (int blk = 0; blk < 4; ++blk) {
;                 const s16x4 lo = __builtin_amdgcn_ds_read_tr16_b64_v4i16((LAS s16x4*)(Vb + s * 4096 + voffs[blk][0]));
;                 const s16x4 hi = __builtin_amdgcn_ds_read_tr16_b64_v4i16((LAS s16x4*)(Vb + s * 4096 + voffs[blk][1]));
;                 const bf16x8 va = __builtin_shufflevector(lo, hi, 0, 1, 2, 3, 4, 5, 6, 7);
;                 O[blk] = MFMA32(va, pf[s], O[blk]);
;             }
;         }
.LBB0_466:
	v_pk_fma_f32 v[96:97], v[96:97], s[20:21], v[0:1] op_sel_hi:[1,0,0] neg_lo:[0,0,1] neg_hi:[0,0,1]
	v_pk_fma_f32 v[98:99], v[98:99], s[20:21], v[0:1] op_sel_hi:[1,0,0] neg_lo:[0,0,1] neg_hi:[0,0,1]
	v_pk_fma_f32 v[100:101], v[100:101], s[20:21], v[0:1] op_sel_hi:[1,0,0] neg_lo:[0,0,1] neg_hi:[0,0,1]
	v_pk_fma_f32 v[102:103], v[102:103], s[20:21], v[0:1] op_sel_hi:[1,0,0] neg_lo:[0,0,1] neg_hi:[0,0,1]
	v_exp_f32_e32 v96, v96
	v_exp_f32_e32 v97, v97
	v_exp_f32_e32 v98, v98
	v_exp_f32_e32 v99, v99
	v_exp_f32_e32 v100, v100
	v_exp_f32_e32 v101, v101
	v_exp_f32_e32 v102, v102
	v_exp_f32_e32 v103, v103
	v_pk_fma_f32 v[104:105], v[104:105], s[20:21], v[0:1] op_sel_hi:[1,0,0] neg_lo:[0,0,1] neg_hi:[0,0,1]
	v_pk_fma_f32 v[106:107], v[106:107], s[20:21], v[0:1] op_sel_hi:[1,0,0] neg_lo:[0,0,1] neg_hi:[0,0,1]
	v_cvt_pk_bf16_f32 v6, v96, v97
	v_cvt_pk_bf16_f32 v7, v98, v99
	v_cvt_pk_bf16_f32 v8, v100, v101
	v_cvt_pk_bf16_f32 v9, v102, v103
	v_pk_fma_f32 v[108:109], v[108:109], s[20:21], v[0:1] op_sel_hi:[1,0,0] neg_lo:[0,0,1] neg_hi:[0,0,1]
	v_pk_fma_f32 v[110:111], v[110:111], s[20:21], v[0:1] op_sel_hi:[1,0,0] neg_lo:[0,0,1] neg_hi:[0,0,1]
	v_pk_add_f32 v[224:225], v[96:97], v[98:99]
	s_waitcnt lgkmcnt(2)
	v_mfma_f32_32x32x16_bf16 v[64:79], v[192:195], v[6:9], v[64:79]
	ds_read_b64_tr_b16 v[192:193], v2 offset:16384
	ds_read_b64_tr_b16 v[194:195], v3 offset:2048
	v_exp_f32_e32 v104, v104
	v_exp_f32_e32 v105, v105
	v_exp_f32_e32 v106, v106
	v_exp_f32_e32 v107, v107
	v_pk_add_f32 v[224:225], v[100:101], v[224:225]
	s_waitcnt lgkmcnt(2)
	v_mfma_f32_32x32x16_bf16 v[48:63], v[196:199], v[6:9], v[48:63]
	ds_read_b64_tr_b16 v[196:197], v4 offset:16384
	ds_read_b64_tr_b16 v[198:199], v5 offset:2048
	v_exp_f32_e32 v108, v108
	v_exp_f32_e32 v109, v109
	v_exp_f32_e32 v110, v110
	v_exp_f32_e32 v111, v111
	v_pk_add_f32 v[224:225], v[102:103], v[224:225]
	s_waitcnt lgkmcnt(2)
	v_mfma_f32_32x32x16_bf16 v[32:47], v[192:195], v[6:9], v[32:47]
	ds_read_b64_tr_b16 v[192:193], v201 offset:20480
	ds_read_b64_tr_b16 v[194:195], v202 offset:6144
	v_cvt_pk_bf16_f32 v10, v104, v105
	v_cvt_pk_bf16_f32 v11, v106, v107
	v_cvt_pk_bf16_f32 v12, v108, v109
	v_cvt_pk_bf16_f32 v13, v110, v111
	v_pk_add_f32 v[224:225], v[104:105], v[224:225]
	s_waitcnt lgkmcnt(2)
	v_mfma_f32_32x32x16_bf16 v[16:31], v[196:199], v[6:9], v[16:31]
	ds_read_b64_tr_b16 v[196:197], v203 offset:20480
	ds_read_b64_tr_b16 v[198:199], v204 offset:6144
	v_pk_add_f32 v[224:225], v[106:107], v[224:225]
	v_pk_fma_f32 v[80:81], v[80:81], s[20:21], v[0:1] op_sel_hi:[1,0,0] neg_lo:[0,0,1] neg_hi:[0,0,1]
	v_pk_fma_f32 v[82:83], v[82:83], s[20:21], v[0:1] op_sel_hi:[1,0,0] neg_lo:[0,0,1] neg_hi:[0,0,1]
	v_pk_fma_f32 v[84:85], v[84:85], s[20:21], v[0:1] op_sel_hi:[1,0,0] neg_lo:[0,0,1] neg_hi:[0,0,1]
	v_pk_fma_f32 v[86:87], v[86:87], s[20:21], v[0:1] op_sel_hi:[1,0,0] neg_lo:[0,0,1] neg_hi:[0,0,1]
	s_waitcnt lgkmcnt(2)
	v_mfma_f32_32x32x16_bf16 v[64:79], v[192:195], v[10:13], v[64:79]
	ds_read_b64_tr_b16 v[192:193], v2 offset:20480
	ds_read_b64_tr_b16 v[194:195], v3 offset:6144
	v_exp_f32_e32 v80, v80
	v_exp_f32_e32 v81, v81
	v_exp_f32_e32 v82, v82
	v_exp_f32_e32 v83, v83
	v_pk_add_f32 v[224:225], v[108:109], v[224:225]
	s_waitcnt lgkmcnt(2)
	v_mfma_f32_32x32x16_bf16 v[48:63], v[196:199], v[10:13], v[48:63]
	ds_read_b64_tr_b16 v[196:197], v4 offset:20480
	ds_read_b64_tr_b16 v[198:199], v5 offset:6144
	v_exp_f32_e32 v84, v84
	v_exp_f32_e32 v85, v85
	v_exp_f32_e32 v86, v86
	v_exp_f32_e32 v87, v87
	v_pk_add_f32 v[224:225], v[110:111], v[224:225]
	s_waitcnt lgkmcnt(2)
	v_mfma_f32_32x32x16_bf16 v[32:47], v[192:195], v[10:13], v[32:47]
	ds_read_b64_tr_b16 v[192:193], v201 offset:24576
	ds_read_b64_tr_b16 v[194:195], v202 offset:10240
	v_cvt_pk_bf16_f32 v6, v80, v81
	v_cvt_pk_bf16_f32 v7, v82, v83
	v_cvt_pk_bf16_f32 v8, v84, v85
	v_cvt_pk_bf16_f32 v9, v86, v87
	v_pk_add_f32 v[224:225], v[80:81], v[224:225]
	s_waitcnt lgkmcnt(2)
	v_mfma_f32_32x32x16_bf16 v[16:31], v[196:199], v[10:13], v[16:31]
	ds_read_b64_tr_b16 v[196:197], v203 offset:24576
	ds_read_b64_tr_b16 v[198:199], v204 offset:10240
	v_pk_add_f32 v[224:225], v[82:83], v[224:225]
	v_pk_fma_f32 v[88:89], v[88:89], s[20:21], v[0:1] op_sel_hi:[1,0,0] neg_lo:[0,0,1] neg_hi:[0,0,1]
	v_pk_fma_f32 v[90:91], v[90:91], s[20:21], v[0:1] op_sel_hi:[1,0,0] neg_lo:[0,0,1] neg_hi:[0,0,1]
	v_pk_fma_f32 v[92:93], v[92:93], s[20:21], v[0:1] op_sel_hi:[1,0,0] neg_lo:[0,0,1] neg_hi:[0,0,1]
	v_pk_fma_f32 v[94:95], v[94:95], s[20:21], v[0:1] op_sel_hi:[1,0,0] neg_lo:[0,0,1] neg_hi:[0,0,1]
	s_waitcnt lgkmcnt(2)
	v_mfma_f32_32x32x16_bf16 v[64:79], v[192:195], v[6:9], v[64:79]
	ds_read_b64_tr_b16 v[192:193], v2 offset:24576
	ds_read_b64_tr_b16 v[194:195], v3 offset:10240
	v_exp_f32_e32 v88, v88
	v_exp_f32_e32 v89, v89
	v_exp_f32_e32 v90, v90
	v_exp_f32_e32 v91, v91
	v_pk_add_f32 v[224:225], v[84:85], v[224:225]
	s_waitcnt lgkmcnt(2)
	v_mfma_f32_32x32x16_bf16 v[48:63], v[196:199], v[6:9], v[48:63]
	ds_read_b64_tr_b16 v[196:197], v4 offset:24576
	ds_read_b64_tr_b16 v[198:199], v5 offset:10240
	v_exp_f32_e32 v92, v92
	v_exp_f32_e32 v93, v93
	v_exp_f32_e32 v94, v94
	v_exp_f32_e32 v95, v95
	v_pk_add_f32 v[224:225], v[86:87], v[224:225]
	s_waitcnt lgkmcnt(2)
	v_mfma_f32_32x32x16_bf16 v[32:47], v[192:195], v[6:9], v[32:47]
	ds_read_b64_tr_b16 v[192:193], v201 offset:28672
	ds_read_b64_tr_b16 v[194:195], v202 offset:14336
	v_cvt_pk_bf16_f32 v10, v88, v89
	v_cvt_pk_bf16_f32 v11, v90, v91
	v_cvt_pk_bf16_f32 v12, v92, v93
	v_cvt_pk_bf16_f32 v13, v94, v95
	v_pk_add_f32 v[224:225], v[88:89], v[224:225]
	s_waitcnt lgkmcnt(2)
	v_mfma_f32_32x32x16_bf16 v[16:31], v[196:199], v[6:9], v[16:31]
	ds_read_b64_tr_b16 v[196:197], v203 offset:28672
	ds_read_b64_tr_b16 v[198:199], v204 offset:14336
	v_pk_add_f32 v[224:225], v[90:91], v[224:225]
	s_waitcnt lgkmcnt(2)
	v_mfma_f32_32x32x16_bf16 v[64:79], v[192:195], v[10:13], v[64:79]
	ds_read_b64_tr_b16 v[192:193], v2 offset:28672
	ds_read_b64_tr_b16 v[194:195], v3 offset:14336
	v_pk_add_f32 v[224:225], v[92:93], v[224:225]
	s_waitcnt lgkmcnt(2)
	v_mfma_f32_32x32x16_bf16 v[48:63], v[196:199], v[10:13], v[48:63]
	ds_read_b64_tr_b16 v[196:197], v4 offset:28672
	ds_read_b64_tr_b16 v[198:199], v5 offset:14336
	v_pk_add_f32 v[224:225], v[94:95], v[224:225]
	s_waitcnt lgkmcnt(2)
	v_mfma_f32_32x32x16_bf16 v[32:47], v[192:195], v[10:13], v[32:47]
	v_add_f32_e32 v15, v224, v225
	s_waitcnt lgkmcnt(0)
	v_mfma_f32_32x32x16_bf16 v[16:31], v[196:199], v[10:13], v[16:31]
	v_fmac_f32_e32 v15, v174, v14
	s_nop 0
	v_mov_b32_e32 v174, v15
	s_cmp_ge_i32 s49, s45
	s_cbranch_scc0 .LBB0_468
	s_branch .LBB0_473
